# P1: modulation-GEMM epilogue loads its bias quads once (32 dependent round trips -> 1), modulation GEMM on 32 blocks, carry-in/end-state operand build loops keep 4 items in flight
# baseline (speedup 1.0000x reference)
; __global__ void __launch_bounds__(512, 2) hybrid_fwd(Params P) {
;     ...
;         if (bid >= 96) {
;         const int gt = (bid - 96) * 512 + tid, NGT = (G - 96) * 512;
;         for (int i = gt; i < DEPTH * 16 * 31 * 256; i += NGT) { const int c = i & 15, cp = (i >> 4) & 15, ti = (i >> 8) % 31, lg = i / (256 * 31); const int tau = ti - 15;
;             bf16_t* by = BTY + (size_t)lg * 256 * KY;
;             if (tau < 0) { for (int t = 0; t <= 15 + tau; ++t) by[(size_t)(t * 16 + cp) * KY + (t - tau) * 16 + c] = 0; }
.LBB0_170:
	s_cmp_lt_i32 s78, 2
	s_cselect_b64 s[0:1], -1, 0
	s_cmp_gt_i32 s79, 1
	s_cselect_b64 s[2:3], -1, 0
	s_and_b64 s[0:1], s[0:1], s[2:3]
	s_andn2_b64 vcc, exec, s[0:1]
	s_cbranch_vccnz .LBB0_303
	s_add_i32 s0, 0, 0x20400
	v_readlane_b32 s28, v253, 1
	v_readlane_b32 s29, v253, 0
	v_readlane_b32 s26, v253, 2
	v_mov_b32_e32 v13, s0
	v_mbcnt_lo_u32_b32 v40, -1, 0
	v_mbcnt_hi_u32_b32 v40, -1, v40
	ds_read_b64 v[0:1], v13 offset:280
	v_lshl_add_u32 v144, s26, 6, v40
	s_cmpk_lt_i32 s29, 0x20
	s_waitcnt lgkmcnt(0)
	v_readfirstlane_b32 s7, v1
	v_readfirstlane_b32 s6, v0
	s_cbranch_scc1 .LBB0_209
	s_lshl_b32 s0, s29, 9
	s_add_i32 s0, s0, 0xffffc000
	v_add_u32_e32 v17, s0, v144
	s_lshl_b32 s27, s28, 9
	s_mov_b32 s0, 0x7c000
	s_add_i32 s27, s27, 0xffffc000
	v_cmp_gt_i32_e32 vcc, s0, v17
	v_and_b32_e32 v12, 15, v40
	s_and_saveexec_b64 s[8:9], vcc
	s_cbranch_execz .LBB0_203
	v_mov_b32_e32 v15, 0
	v_lshlrev_b32_e32 v14, 1, v12
	s_mov_b64 s[0:1], 0x1c00000
	s_add_u32 s10, s6, 0x1c00000
	v_lshl_add_u64 v[0:1], s[6:7], 0, v[14:15]
	s_addc_u32 s11, s7, 0
	v_lshlrev_b32_e32 v16, 3, v12
	v_lshl_add_u64 v[18:19], v[0:1], 0, s[0:1]
	s_mov_b64 s[12:13], 0
	s_mov_b32 s30, 0x84210843
	s_mov_b64 s[14:15], 0x400000
	s_mov_b64 s[16:17], 0x200
	s_brev_b32 s31, 8
	s_movk_i32 s33, 0x300
	v_lshlrev_b32_e32 v14, 1, v12
	s_mov_b32 s34, 0x7bfff
	v_mov_b32_e32 v41, 0xf0
	v_mov_b32_e32 v42, v17
	s_branch .LBB0_176

; __device__ __forceinline__ bf16_t f2bf(float f) { return (bf16_t)(cvt_pk_bf16(f, 0.f) & 0xffffu); }
; #define INP(i) ((const float*)ld_ptr(pb, (i)))
; __global__ void __launch_bounds__(512, 2) hybrid_fwd(Params P) {
;     ...
;         for (int i = gt; i < DEPTH * 16 * 16 * 16 * 64; i += NGT) { const int p = i & 63, cp = (i >> 6) & 15, t = (i >> 10) & 15, lg = i >> 14;
;             const float ar = APOW[(((size_t)lg * 17 + t + 1) * 64 + p) * 2], ai = APOW[(((size_t)lg * 17 + t + 1) * 64 + p) * 2 + 1];
;             const float cr = INP(20)[((size_t)lg * 16 + cp) * 64 + p], ci = INP(21)[((size_t)lg * 16 + cp) * 64 + p];
;             bf16_t* by = BTY + ((size_t)lg * 256 + t * 16 + cp) * KY + 256; by[p] = f2bf(cr * ar - ci * ai); by[64 + p] = f2bf(-(cr * ai + ci * ar)); }
.LBB0_203:
	s_or_b64 exec, exec, s[8:9]
	s_mov_b32 s0, 0x100000
	v_cmp_gt_i32_e32 vcc, s0, v17
	s_and_saveexec_b64 s[0:1], vcc
	s_cbranch_execz .LBB0_208
	ds_read2_b64 v[0:3], v13 offset0:20 offset1:21
	s_add_u32 s2, s6, 0x400000
	v_and_b32_e32 v4, 63, v40
	v_mov_b32_e32 v7, 0
	s_addc_u32 s3, s7, 0
	s_mov_b64 s[4:5], 0
	s_movk_i32 s10, 0x300
	v_mov_b64_e32 v[8:9], s[6:7]
	v_lshlrev_b32_e32 v10, 1, v4
	v_mov_b32_e32 v11, v7
	s_mov_b64 s[8:9], 0x1c00200
	s_mov_b32 s11, 0xfffff
	v_mov_b32_e32 v5, v17
	s_waitcnt lgkmcnt(0)
	v_readfirstlane_b32 s80, v0
	v_readfirstlane_b32 s81, v1
	v_readfirstlane_b32 s82, v2
	v_readfirstlane_b32 s83, v3
	s_lshl_b32 s90, s27, 2
	s_mov_b64 s[92:93], exec
	s_mov_b64 s[84:85], exec
	v_mov_b32_e32 v105, v17
	v_mov_b32_e32 v107, 0
	v_add_u32_e32 v137, s27, v105
	v_mov_b32_e32 v139, 0
	v_add_u32_e32 v169, s27, v137
	v_mov_b32_e32 v171, 0
	v_add_u32_e32 v201, s27, v169
	v_mov_b32_e32 v203, 0
.Lmy_b2_loop:
	v_cmp_ge_i32_e64 s[66:67], s11, v105
	s_and_b64 exec, s[84:85], s[66:67]
	v_ashrrev_i32_e32 v114, 14, v105
	v_bfe_u32 v106, v105, 10, 4
	v_ashrrev_i32_e32 v115, 31, v114
	v_mul_hi_i32_i24_e32 v119, 17, v114
	v_mul_i32_i24_e32 v118, 17, v114
	v_bfe_u32 v116, v105, 6, 4
	v_lshl_add_u64 v[118:119], v[118:119], 0, v[106:107]
	v_lshlrev_b64 v[120:121], 10, v[114:115]
	v_lshlrev_b64 v[118:119], 9, v[118:119]
	v_lshl_or_b32 v115, v116, 6, v120
	v_lshl_or_b32 v118, v4, 3, v118
	v_or_b32_e32 v120, v115, v4
	v_lshl_add_u64 v[118:119], s[2:3], 0, v[118:119]
	v_lshlrev_b64 v[120:121], 2, v[120:121]
	global_load_dwordx2 v[118:119], v[118:119], off offset:512
	v_lshl_add_u64 v[122:123], s[80:81], 0, v[120:121]
	v_lshl_add_u64 v[120:121], s[82:83], 0, v[120:121]
	global_load_dword v124, v[120:121], off
	global_load_dword v125, v[122:123], off
	v_cmp_ge_i32_e64 s[68:69], s11, v137
	s_and_b64 exec, s[84:85], s[68:69]
	v_ashrrev_i32_e32 v146, 14, v137
	v_bfe_u32 v138, v137, 10, 4
	v_ashrrev_i32_e32 v147, 31, v146
	v_mul_hi_i32_i24_e32 v151, 17, v146
	v_mul_i32_i24_e32 v150, 17, v146
	v_bfe_u32 v148, v137, 6, 4
	v_lshl_add_u64 v[150:151], v[150:151], 0, v[138:139]
	v_lshlrev_b64 v[152:153], 10, v[146:147]
	v_lshlrev_b64 v[150:151], 9, v[150:151]
	v_lshl_or_b32 v147, v148, 6, v152
	v_lshl_or_b32 v150, v4, 3, v150
	v_or_b32_e32 v152, v147, v4
	v_lshl_add_u64 v[150:151], s[2:3], 0, v[150:151]
	v_lshlrev_b64 v[152:153], 2, v[152:153]
	global_load_dwordx2 v[150:151], v[150:151], off offset:512
	v_lshl_add_u64 v[154:155], s[80:81], 0, v[152:153]
	v_lshl_add_u64 v[152:153], s[82:83], 0, v[152:153]
	global_load_dword v156, v[152:153], off
	global_load_dword v157, v[154:155], off
	v_cmp_ge_i32_e64 s[70:71], s11, v169
	s_and_b64 exec, s[84:85], s[70:71]
	v_ashrrev_i32_e32 v178, 14, v169
	v_bfe_u32 v170, v169, 10, 4
	v_ashrrev_i32_e32 v179, 31, v178
	v_mul_hi_i32_i24_e32 v183, 17, v178
	v_mul_i32_i24_e32 v182, 17, v178
	v_bfe_u32 v180, v169, 6, 4
	v_lshl_add_u64 v[182:183], v[182:183], 0, v[170:171]
	v_lshlrev_b64 v[184:185], 10, v[178:179]
	v_lshlrev_b64 v[182:183], 9, v[182:183]
	v_lshl_or_b32 v179, v180, 6, v184
	v_lshl_or_b32 v182, v4, 3, v182
	v_or_b32_e32 v184, v179, v4
	v_lshl_add_u64 v[182:183], s[2:3], 0, v[182:183]
	v_lshlrev_b64 v[184:185], 2, v[184:185]
	global_load_dwordx2 v[182:183], v[182:183], off offset:512
	v_lshl_add_u64 v[186:187], s[80:81], 0, v[184:185]
	v_lshl_add_u64 v[184:185], s[82:83], 0, v[184:185]
	global_load_dword v188, v[184:185], off
	global_load_dword v189, v[186:187], off
	v_cmp_ge_i32_e64 s[72:73], s11, v201
	s_and_b64 exec, s[84:85], s[72:73]
	v_ashrrev_i32_e32 v210, 14, v201
	v_bfe_u32 v202, v201, 10, 4
	v_ashrrev_i32_e32 v211, 31, v210
	v_mul_hi_i32_i24_e32 v215, 17, v210
	v_mul_i32_i24_e32 v214, 17, v210
	v_bfe_u32 v212, v201, 6, 4
	v_lshl_add_u64 v[214:215], v[214:215], 0, v[202:203]
	v_lshlrev_b64 v[216:217], 10, v[210:211]
	v_lshlrev_b64 v[214:215], 9, v[214:215]
	v_lshl_or_b32 v211, v212, 6, v216
	v_lshl_or_b32 v214, v4, 3, v214
	v_or_b32_e32 v216, v211, v4
	v_lshl_add_u64 v[214:215], s[2:3], 0, v[214:215]
	v_lshlrev_b64 v[216:217], 2, v[216:217]
	global_load_dwordx2 v[214:215], v[214:215], off offset:512
	v_lshl_add_u64 v[218:219], s[80:81], 0, v[216:217]
	v_lshl_add_u64 v[216:217], s[82:83], 0, v[216:217]
	global_load_dword v220, v[216:217], off
	global_load_dword v221, v[218:219], off
	s_mov_b64 exec, s[84:85]
	s_waitcnt vmcnt(0)
; __device__ __forceinline__ bf16_t f2bf(float f) { return (bf16_t)(cvt_pk_bf16(f, 0.f) & 0xffffu); }
; #define INP(i) ((const float*)ld_ptr(pb, (i)))
; __global__ void __launch_bounds__(512, 2) hybrid_fwd(Params P) {
;     ...
;         for (int i = gt; i < DEPTH * 16 * 16 * 16 * 64; i += NGT) { const int p = i & 63, cp = (i >> 6) & 15, t = (i >> 10) & 15, lg = i >> 14;
;             const float ar = APOW[(((size_t)lg * 17 + t + 1) * 64 + p) * 2], ai = APOW[(((size_t)lg * 17 + t + 1) * 64 + p) * 2 + 1];
;             const float cr = INP(20)[((size_t)lg * 16 + cp) * 64 + p], ci = INP(21)[((size_t)lg * 16 + cp) * 64 + p];
;             bf16_t* by = BTY + ((size_t)lg * 256 + t * 16 + cp) * KY + 256; by[p] = f2bf(cr * ar - ci * ai); by[64 + p] = f2bf(-(cr * ai + ci * ar)); }
;         for (int i = gt; i < DEPTH * 16 * 64 * 256; i += NGT) { const int c = i & 15, s = (i >> 4) & 15, p = (i >> 8) & 63, lg = i >> 14;
;             const float ar = APOW[(((size_t)lg * 17 + 15 - s) * 64 + p) * 2], ai = APOW[(((size_t)lg * 17 + 15 - s) * 64 + p) * 2 + 1];
;             const float br = BB[(((size_t)lg * 64 + p) * 16 + c) * 2], bi = BB[(((size_t)lg * 64 + p) * 16 + c) * 2 + 1];
;             bf16_t* be = BTE + ((size_t)lg * 128 + p) * 256 + s * 16 + c; be[0] = f2bf(ar * br - ai * bi); be[(size_t)64 * 256] = f2bf(ar * bi + ai * br); }
	s_and_b64 exec, s[84:85], s[66:67]
	v_lshlrev_b32_e32 v114, 8, v114
	v_lshlrev_b32_e32 v106, 4, v106
	v_or3_b32 v106, v114, v106, v116
	v_mad_i64_i32 v[114:115], s[12:13], v106, s10, v[8:9]
	v_lshl_add_u64 v[114:115], v[114:115], 0, v[10:11]
	v_lshl_add_u64 v[120:121], v[114:115], 0, s[8:9]
	v_add_co_u32_e32 v114, vcc, 0x1c00000, v114
	v_mul_f32_e32 v106, v119, v124
	v_mul_f32_e32 v116, v118, v124
	v_fma_f32 v106, v118, v125, -v106
	v_addc_co_u32_e32 v115, vcc, 0, v115, vcc
	v_fmac_f32_e32 v116, v119, v125
	v_cvt_pk_bf16_f32 v106, v106, s0
	v_cvt_pk_bf16_f32 v116, -v116, s0
	global_store_short v[114:115], v106, off offset:512
	global_store_short v[120:121], v116, off offset:128
	s_and_b64 exec, s[84:85], s[68:69]
	v_lshlrev_b32_e32 v146, 8, v146
	v_lshlrev_b32_e32 v138, 4, v138
	v_or3_b32 v138, v146, v138, v148
	v_mad_i64_i32 v[146:147], s[12:13], v138, s10, v[8:9]
	v_lshl_add_u64 v[146:147], v[146:147], 0, v[10:11]
	v_lshl_add_u64 v[152:153], v[146:147], 0, s[8:9]
	v_add_co_u32_e32 v146, vcc, 0x1c00000, v146
	v_mul_f32_e32 v138, v151, v156
	v_mul_f32_e32 v148, v150, v156
	v_fma_f32 v138, v150, v157, -v138
	v_addc_co_u32_e32 v147, vcc, 0, v147, vcc
	v_fmac_f32_e32 v148, v151, v157
	v_cvt_pk_bf16_f32 v138, v138, s0
	v_cvt_pk_bf16_f32 v148, -v148, s0
	global_store_short v[146:147], v138, off offset:512
	global_store_short v[152:153], v148, off offset:128
	s_and_b64 exec, s[84:85], s[70:71]
	v_lshlrev_b32_e32 v178, 8, v178
	v_lshlrev_b32_e32 v170, 4, v170
	v_or3_b32 v170, v178, v170, v180
	v_mad_i64_i32 v[178:179], s[12:13], v170, s10, v[8:9]
	v_lshl_add_u64 v[178:179], v[178:179], 0, v[10:11]
	v_lshl_add_u64 v[184:185], v[178:179], 0, s[8:9]
	v_add_co_u32_e32 v178, vcc, 0x1c00000, v178
	v_mul_f32_e32 v170, v183, v188
	v_mul_f32_e32 v180, v182, v188
	v_fma_f32 v170, v182, v189, -v170
	v_addc_co_u32_e32 v179, vcc, 0, v179, vcc
	v_fmac_f32_e32 v180, v183, v189
	v_cvt_pk_bf16_f32 v170, v170, s0
	v_cvt_pk_bf16_f32 v180, -v180, s0
	global_store_short v[178:179], v170, off offset:512
	global_store_short v[184:185], v180, off offset:128
	s_and_b64 exec, s[84:85], s[72:73]
	v_lshlrev_b32_e32 v210, 8, v210
	v_lshlrev_b32_e32 v202, 4, v202
	v_or3_b32 v202, v210, v202, v212
	v_mad_i64_i32 v[210:211], s[12:13], v202, s10, v[8:9]
	v_lshl_add_u64 v[210:211], v[210:211], 0, v[10:11]
	v_lshl_add_u64 v[216:217], v[210:211], 0, s[8:9]
	v_add_co_u32_e32 v210, vcc, 0x1c00000, v210
	v_mul_f32_e32 v202, v215, v220
	v_mul_f32_e32 v212, v214, v220
	v_fma_f32 v202, v214, v221, -v202
	v_addc_co_u32_e32 v211, vcc, 0, v211, vcc
	v_fmac_f32_e32 v212, v215, v221
	v_cvt_pk_bf16_f32 v202, v202, s0
	v_cvt_pk_bf16_f32 v212, -v212, s0
	global_store_short v[210:211], v202, off offset:512
	global_store_short v[216:217], v212, off offset:128
	s_mov_b64 exec, s[84:85]
	v_add_u32_e32 v105, s90, v105
	v_add_u32_e32 v137, s90, v137
	v_add_u32_e32 v169, s90, v169
	v_add_u32_e32 v201, s90, v201
	v_cmp_ge_i32_e32 vcc, s11, v105
	s_and_b64 s[84:85], s[84:85], vcc
	s_mov_b64 exec, s[84:85]
	s_cbranch_execnz .Lmy_b2_loop
	s_mov_b64 exec, s[92:93]
	s_or_b64 exec, exec, s[4:5]
	s_add_u32 s4, s6, 0x500000
	s_addc_u32 s5, s7, 0
	s_add_u32 s8, s6, 0x1700000
	v_mov_b32_e32 v1, 0
	s_addc_u32 s9, s7, 0
	s_mov_b64 s[10:11], 0
	s_movk_i32 s12, 0x1000
	v_lshlrev_b32_e32 v2, 1, v12
	v_mov_b32_e32 v3, v1
	s_mov_b32 s13, 0xfffff
	s_lshl_b32 s90, s27, 2
	s_mov_b64 s[92:93], exec
	s_mov_b64 s[84:85], exec
	v_mov_b32_e32 v117, v17
	v_mov_b32_e32 v101, 0
	v_add_u32_e32 v149, s27, v117
	v_mov_b32_e32 v133, 0
	v_add_u32_e32 v181, s27, v149
	v_mov_b32_e32 v165, 0
	v_add_u32_e32 v213, s27, v181
	v_mov_b32_e32 v197, 0
; __device__ __forceinline__ bf16_t f2bf(float f) { return (bf16_t)(cvt_pk_bf16(f, 0.f) & 0xffffu); }
; __global__ void __launch_bounds__(512, 2) hybrid_fwd(Params P) {
;     ...
;         for (int i = gt; i < DEPTH * 16 * 64 * 256; i += NGT) { const int c = i & 15, s = (i >> 4) & 15, p = (i >> 8) & 63, lg = i >> 14;
;             const float ar = APOW[(((size_t)lg * 17 + 15 - s) * 64 + p) * 2], ai = APOW[(((size_t)lg * 17 + 15 - s) * 64 + p) * 2 + 1];
;             const float br = BB[(((size_t)lg * 64 + p) * 16 + c) * 2], bi = BB[(((size_t)lg * 64 + p) * 16 + c) * 2 + 1];
;             bf16_t* be = BTE + ((size_t)lg * 128 + p) * 256 + s * 16 + c; be[0] = f2bf(ar * br - ai * bi); be[(size_t)64 * 256] = f2bf(ar * bi + ai * br); }
.Lmy_b3_loop:
	v_cmp_ge_i32_e64 s[66:67], s13, v117
	s_and_b64 exec, s[84:85], s[66:67]
	v_ashrrev_i32_e32 v104, 14, v117
	v_bfe_u32 v116, v117, 4, 4
	v_mul_i32_i24_e32 v106, 17, v104
	v_mul_hi_i32_i24_e32 v107, 17, v104
	v_sub_co_u32_e32 v106, vcc, v106, v116
	v_ashrrev_i32_e32 v105, 31, v104
	s_nop 0
	v_subbrev_co_u32_e32 v107, vcc, 0, v107, vcc
	v_bfe_u32 v118, v117, 8, 6
	v_lshlrev_b64 v[108:109], 10, v[104:105]
	v_lshlrev_b64 v[106:107], 9, v[106:107]
	v_lshlrev_b32_e32 v100, 3, v118
	v_lshl_or_b32 v108, v118, 4, v108
	v_lshl_add_u64 v[106:107], s[2:3], 0, v[106:107]
	v_or_b32_e32 v108, v108, v12
	v_lshl_add_u64 v[106:107], v[106:107], 0, v[100:101]
	v_lshl_add_u64 v[108:109], v[108:109], 3, s[4:5]
	v_add_co_u32_e32 v106, vcc, s12, v106
	v_lshlrev_b64 v[104:105], 16, v[104:105]
	s_nop 0
	v_addc_co_u32_e32 v107, vcc, 0, v107, vcc
	global_load_dwordx2 v[110:111], v[108:109], off
	global_load_dwordx2 v[114:115], v[106:107], off offset:3584
	v_cmp_ge_i32_e64 s[68:69], s13, v149
	s_and_b64 exec, s[84:85], s[68:69]
	v_ashrrev_i32_e32 v136, 14, v149
	v_bfe_u32 v148, v149, 4, 4
	v_mul_i32_i24_e32 v138, 17, v136
	v_mul_hi_i32_i24_e32 v139, 17, v136
	v_sub_co_u32_e32 v138, vcc, v138, v148
	v_ashrrev_i32_e32 v137, 31, v136
	s_nop 0
	v_subbrev_co_u32_e32 v139, vcc, 0, v139, vcc
	v_bfe_u32 v150, v149, 8, 6
	v_lshlrev_b64 v[140:141], 10, v[136:137]
	v_lshlrev_b64 v[138:139], 9, v[138:139]
	v_lshlrev_b32_e32 v132, 3, v150
	v_lshl_or_b32 v140, v150, 4, v140
	v_lshl_add_u64 v[138:139], s[2:3], 0, v[138:139]
	v_or_b32_e32 v140, v140, v12
	v_lshl_add_u64 v[138:139], v[138:139], 0, v[132:133]
	v_lshl_add_u64 v[140:141], v[140:141], 3, s[4:5]
	v_add_co_u32_e32 v138, vcc, s12, v138
	v_lshlrev_b64 v[136:137], 16, v[136:137]
	s_nop 0
	v_addc_co_u32_e32 v139, vcc, 0, v139, vcc
	global_load_dwordx2 v[142:143], v[140:141], off
	global_load_dwordx2 v[146:147], v[138:139], off offset:3584
	v_cmp_ge_i32_e64 s[70:71], s13, v181
	s_and_b64 exec, s[84:85], s[70:71]
	v_ashrrev_i32_e32 v168, 14, v181
	v_bfe_u32 v180, v181, 4, 4
	v_mul_i32_i24_e32 v170, 17, v168
	v_mul_hi_i32_i24_e32 v171, 17, v168
	v_sub_co_u32_e32 v170, vcc, v170, v180
	v_ashrrev_i32_e32 v169, 31, v168
	s_nop 0
	v_subbrev_co_u32_e32 v171, vcc, 0, v171, vcc
	v_bfe_u32 v182, v181, 8, 6
	v_lshlrev_b64 v[172:173], 10, v[168:169]
	v_lshlrev_b64 v[170:171], 9, v[170:171]
	v_lshlrev_b32_e32 v164, 3, v182
	v_lshl_or_b32 v172, v182, 4, v172
	v_lshl_add_u64 v[170:171], s[2:3], 0, v[170:171]
	v_or_b32_e32 v172, v172, v12
	v_lshl_add_u64 v[170:171], v[170:171], 0, v[164:165]
	v_lshl_add_u64 v[172:173], v[172:173], 3, s[4:5]
	v_add_co_u32_e32 v170, vcc, s12, v170
	v_lshlrev_b64 v[168:169], 16, v[168:169]
	s_nop 0
	v_addc_co_u32_e32 v171, vcc, 0, v171, vcc
	global_load_dwordx2 v[174:175], v[172:173], off
	global_load_dwordx2 v[178:179], v[170:171], off offset:3584
	v_cmp_ge_i32_e64 s[72:73], s13, v213
	s_and_b64 exec, s[84:85], s[72:73]
	v_ashrrev_i32_e32 v200, 14, v213
	v_bfe_u32 v212, v213, 4, 4
	v_mul_i32_i24_e32 v202, 17, v200
	v_mul_hi_i32_i24_e32 v203, 17, v200
	v_sub_co_u32_e32 v202, vcc, v202, v212
	v_ashrrev_i32_e32 v201, 31, v200
	s_nop 0
	v_subbrev_co_u32_e32 v203, vcc, 0, v203, vcc
	v_bfe_u32 v214, v213, 8, 6
	v_lshlrev_b64 v[204:205], 10, v[200:201]
	v_lshlrev_b64 v[202:203], 9, v[202:203]
	v_lshlrev_b32_e32 v196, 3, v214
	v_lshl_or_b32 v204, v214, 4, v204
	v_lshl_add_u64 v[202:203], s[2:3], 0, v[202:203]
	v_or_b32_e32 v204, v204, v12
	v_lshl_add_u64 v[202:203], v[202:203], 0, v[196:197]
	v_lshl_add_u64 v[204:205], v[204:205], 3, s[4:5]
	v_add_co_u32_e32 v202, vcc, s12, v202
	v_lshlrev_b64 v[200:201], 16, v[200:201]
	s_nop 0
	v_addc_co_u32_e32 v203, vcc, 0, v203, vcc
	global_load_dwordx2 v[206:207], v[204:205], off
	global_load_dwordx2 v[210:211], v[202:203], off offset:3584
	s_mov_b64 exec, s[84:85]
	s_waitcnt vmcnt(0)
	s_and_b64 exec, s[84:85], s[66:67]
	v_lshl_add_u64 v[104:105], s[8:9], 0, v[104:105]
	v_lshlrev_b32_e32 v100, 9, v118
	v_lshl_add_u64 v[104:105], v[104:105], 0, v[100:101]
	v_lshlrev_b32_e32 v100, 5, v116
	v_lshl_add_u64 v[104:105], v[104:105], 0, v[100:101]
	v_lshl_add_u64 v[104:105], v[104:105], 0, v[2:3]
	v_add_co_u32_e32 v106, vcc, 0x8000, v104
	v_mul_f32_e32 v100, v115, v111
	v_mul_f32_e32 v108, v114, v111
	v_fma_f32 v100, v114, v110, -v100
	v_fmac_f32_e32 v108, v115, v110
	v_cvt_pk_bf16_f32 v100, v100, s0
	v_addc_co_u32_e32 v107, vcc, 0, v105, vcc
	v_cvt_pk_bf16_f32 v108, v108, s0
	global_store_short v[104:105], v100, off
	global_store_short v[106:107], v108, off
	s_and_b64 exec, s[84:85], s[68:69]
	v_lshl_add_u64 v[136:137], s[8:9], 0, v[136:137]
	v_lshlrev_b32_e32 v132, 9, v150
	v_lshl_add_u64 v[136:137], v[136:137], 0, v[132:133]
	v_lshlrev_b32_e32 v132, 5, v148
	v_lshl_add_u64 v[136:137], v[136:137], 0, v[132:133]
	v_lshl_add_u64 v[136:137], v[136:137], 0, v[2:3]
	v_add_co_u32_e32 v138, vcc, 0x8000, v136
	v_mul_f32_e32 v132, v147, v143
	v_mul_f32_e32 v140, v146, v143
	v_fma_f32 v132, v146, v142, -v132
	v_fmac_f32_e32 v140, v147, v142
	v_cvt_pk_bf16_f32 v132, v132, s0
	v_addc_co_u32_e32 v139, vcc, 0, v137, vcc
	v_cvt_pk_bf16_f32 v140, v140, s0
	global_store_short v[136:137], v132, off
	global_store_short v[138:139], v140, off
	s_and_b64 exec, s[84:85], s[70:71]
	v_lshl_add_u64 v[168:169], s[8:9], 0, v[168:169]
	v_lshlrev_b32_e32 v164, 9, v182
	v_lshl_add_u64 v[168:169], v[168:169], 0, v[164:165]
	v_lshlrev_b32_e32 v164, 5, v180
	v_lshl_add_u64 v[168:169], v[168:169], 0, v[164:165]
	v_lshl_add_u64 v[168:169], v[168:169], 0, v[2:3]
	v_add_co_u32_e32 v170, vcc, 0x8000, v168
	v_mul_f32_e32 v164, v179, v175
	v_mul_f32_e32 v172, v178, v175
	v_fma_f32 v164, v178, v174, -v164
	v_fmac_f32_e32 v172, v179, v174
	v_cvt_pk_bf16_f32 v164, v164, s0
	v_addc_co_u32_e32 v171, vcc, 0, v169, vcc
	v_cvt_pk_bf16_f32 v172, v172, s0
	global_store_short v[168:169], v164, off
	global_store_short v[170:171], v172, off
	s_and_b64 exec, s[84:85], s[72:73]
	v_lshl_add_u64 v[200:201], s[8:9], 0, v[200:201]
	v_lshlrev_b32_e32 v196, 9, v214
	v_lshl_add_u64 v[200:201], v[200:201], 0, v[196:197]
	v_lshlrev_b32_e32 v196, 5, v212
	v_lshl_add_u64 v[200:201], v[200:201], 0, v[196:197]
	v_lshl_add_u64 v[200:201], v[200:201], 0, v[2:3]
	v_add_co_u32_e32 v202, vcc, 0x8000, v200
	v_mul_f32_e32 v196, v211, v207
	v_mul_f32_e32 v204, v210, v207
	v_fma_f32 v196, v210, v206, -v196
	v_fmac_f32_e32 v204, v211, v206
	v_cvt_pk_bf16_f32 v196, v196, s0
	v_addc_co_u32_e32 v203, vcc, 0, v201, vcc
	v_cvt_pk_bf16_f32 v204, v204, s0
	global_store_short v[200:201], v196, off
	global_store_short v[202:203], v204, off
	s_mov_b64 exec, s[84:85]
	v_add_u32_e32 v117, s90, v117
	v_add_u32_e32 v149, s90, v149
	v_add_u32_e32 v181, s90, v181
	v_add_u32_e32 v213, s90, v213
	v_cmp_ge_i32_e32 vcc, s13, v117
	s_and_b64 s[84:85], s[84:85], vcc
	s_mov_b64 exec, s[84:85]
	s_cbranch_execnz .Lmy_b3_loop
	s_mov_b64 exec, s[92:93]

; #define INP(i) ((const float*)ld_ptr(pb, (i)))
; __global__ void __launch_bounds__(512, 2) hybrid_fwd(Params P) {
;     ...
;         __syncthreads();
;         pg8::Gemm g{SC, WMOD, D, D, D, 0, (size_t)6144 * D * 2}; pg8::Order S; S.init(1, 24, DEPTH, G, bid, D / 64);
;         EpiMod E{MOD, INP(12)};
;         pg8::gemm_phase<EpiMod, true>(ldsl, g, S, E, wave);
.LBB0_209:
	s_barrier
	ds_read_b64 v[0:1], v13 offset:96
	s_cmpk_lt_u32 s29, 0x20
	s_cselect_b64 s[0:1], -1, 0
	s_cmpk_gt_u32 s29, 0x1f
	v_mbcnt_lo_u32_b32 v4, -1, 0
	v_mbcnt_hi_u32_b32 v4, -1, v4
	s_waitcnt lgkmcnt(0)
	v_readfirstlane_b32 s30, v1
	v_readfirstlane_b32 s31, v0
	s_cbranch_scc1 .LBB0_212
	s_and_b32 s2, s29, 0xff
	s_mulk_i32 s2, 0xab
	s_lshr_b32 s51, s2, 12
	s_mul_i32 s2, s51, 24
	s_sub_i32 s2, s29, s2
	s_and_b32 s3, s2, 7
	s_bfe_u32 s2, s2, 0x50003
	s_mul_i32 s3, s3, 3
	s_add_i32 s3, s3, s2
	s_and_b32 s18, s3, 63
	s_andn2_b64 vcc, exec, s[0:1]
	s_cbranch_vccz .LBB0_213

;     __device__ bool next(int i, Unit& u) const {
;         const long L = (long)i * G + c; if (c < 0 || L >= tot) return false;
;         if (nsplit > 0 && L >= nwg) { const int r = (int)L - nwg, su = r / nsplit, sp = r % nsplit; u.pm = nMfull + su / nN; u.pn = su % nN; u.z = 0; u.k0 = sp * 256; u.nt = 4; u.split = 1; return true; }
;         const int z = (int)(L / nwg); int wgid = (int)(L % nwg);
;         { const int q = nwg / NXCD, r = nwg % NXCD, xcd = wgid % NXCD, off = wgid / NXCD; wgid = (xcd < r ? xcd * (q + 1) : r * (q + 1) + (xcd - r) * q) + off; }
;         const int nig = WGM * nN, gid = wgid / nig, fm = gid * WGM, gsz = (nM - fm) < WGM ? (nM - fm) : WGM;
;         u.pm = fm + ((wgid % nig) % gsz); u.pn = (wgid % nig) / gsz; u.z = z; u.k0 = 0; u.nt = ntK; u.split = 0; return true;
.LBB0_218:
	s_add_i32 s40, s40, 1
	s_mul_i32 s0, s40, s46
	s_mul_hi_u32 s1, s40, 32
	s_add_i32 s1, s1, s0
	s_mul_i32 s0, s40, 32
	s_add_u32 s0, s0, s29
	s_addc_u32 s1, s1, 0
	v_cmp_gt_i64_e32 vcc, s[0:1], v[138:139]
	v_cmp_lt_i64_e64 s[2:3], s[0:1], v[136:137]
	s_cbranch_vccnz .LBB0_224
	s_mul_i32 s22, s1, 0xaaaaaaab
	s_mul_hi_u32 s23, s0, 0xaaaaaaab
	s_mul_hi_u32 s19, s1, 0xaaaaaaab
	s_add_u32 s22, s22, s23
	s_mul_i32 s17, s0, 0x2aaaaaaa
	s_addc_u32 s19, s19, 0
	s_mul_hi_u32 s16, s0, 0x2aaaaaaa
	s_add_u32 s17, s17, s22
	s_addc_u32 s16, s16, 0
	s_add_u32 s16, s19, s16
	s_addc_u32 s17, 0, 0
	s_mul_i32 s22, s1, 0x2aaaaaaa
	s_mul_hi_u32 s19, s1, 0x2aaaaaaa
	s_add_u32 s16, s22, s16
	s_addc_u32 s17, s19, s17
	s_ashr_i32 s1, s1, 31
	s_mul_i32 s19, s1, 0x2aaaaaaa
	s_mul_hi_u32 s22, s1, 0xaaaaaaab
	s_add_i32 s19, s22, s19
	s_mul_i32 s1, s1, 0xaaaaaaab
	s_add_i32 s19, s19, s1
	s_add_u32 s16, s16, s1
	s_addc_u32 s17, s17, s19
	s_ashr_i64 s[22:23], s[16:17], 2
	s_lshr_b32 s1, s17, 31
	s_add_u32 s50, s22, s1
	s_mul_i32 s1, s50, 24
	s_sub_i32 s0, s0, s1
	s_bfe_i32 s1, s0, 0x80000
	s_bfe_u32 s1, s1, 0x3000c
	s_add_i32 s16, s0, s1
	s_and_b32 s1, s16, 0xf8
	s_sub_i32 s0, s0, s1
	s_bfe_i32 s19, s0, 0x80000
	s_sext_i32_i16 s0, s19
	s_cmp_gt_i32 s0, -1
	s_mov_b64 s[0:1], -1
	s_cbranch_scc0 .LBB0_221
	s_mul_i32 s17, s19, 3
	s_mov_b64 s[0:1], 0

;     __device__ __forceinline__ void operator()(const Acc& acc, const Unit& u, int wr, int wc, int fr, int fq) const {
; #pragma unroll
;         for (int ai = 0; ai < 2; ++ai)
; #pragma unroll
;             for (int m = 0; m < 4; ++m) { const int row = ai * 128 + wr * 64 + m * 16 + fr;
;                 if (row < NMODROWS) {
; #pragma unroll
;                     for (int bj = 0; bj < 2; ++bj)
; #pragma unroll
;                         for (int n = 0; n < 2; ++n) { const int col = u.pn * 256 + bj * 128 + wc * 32 + n * 16 + fq * 4;
;                             const f32x4 b = *(const f32x4*)(bmod + (size_t)u.z * 6144 + col);
;                             *(f32x4*)(mod + ((size_t)u.z * NMODROWS + row) * 6144 + col) = acc[ai][bj][m][n] + b; } } }
;     }
.LBB0_230:
	v_mov_b32_e32 v140, v145
	v_mov_b32_e32 v141, v146
	s_lshl_b32 s17, s18, 8
	s_or_b32 s17, s17, s43
	v_add_u32_e32 v142, s42, v140
	v_lshl_add_u32 v140, v141, 2, s17
	s_mul_hi_i32 s17, s51, 0x6000
	s_mul_i32 s22, s51, 0x6000
	s_mul_hi_i32 s19, s51, 0x84
	s_mul_i32 s18, s51, 0x84
	v_ashrrev_i32_e32 v141, 31, v140
	s_add_u32 s20, s31, s22
	s_addc_u32 s21, s30, s17
	v_lshlrev_b64 v[180:181], 2, v[140:141]
	v_lshl_add_u64 v[180:181], s[20:21], 0, v[180:181]
	global_load_dwordx4 v[164:167], v[180:181], off
	global_load_dwordx4 v[168:171], v[180:181], off offset:64
	global_load_dwordx4 v[172:175], v[180:181], off offset:512
	global_load_dwordx4 v[176:179], v[180:181], off offset:576
	v_cmp_gt_i32_e32 vcc, s49, v142
	s_waitcnt vmcnt(0)
	s_and_saveexec_b64 s[20:21], vcc
	s_cbranch_execz .LBB0_232
	v_lshlrev_b64 v[156:157], 2, v[140:141]
	v_ashrrev_i32_e32 v143, 31, v142
	v_mov_b64_e32 v[160:161], s[10:11]
	v_lshl_add_u64 v[162:163], s[18:19], 0, v[142:143]
	v_mad_u64_u32 v[160:161], s[24:25], v162, s41, v[160:161]
	v_mov_b32_e32 v162, v161
	v_mad_u64_u32 v[162:163], s[24:25], v163, s41, v[162:163]
	v_mov_b32_e32 v161, v162
	v_lshl_add_u64 v[156:157], v[160:161], 0, v[156:157]
	v_pk_add_f32 v[126:127], v[126:127], v[166:167]
	v_pk_add_f32 v[124:125], v[124:125], v[164:165]
	global_store_dwordx4 v[156:157], v[124:127], off
	v_pk_add_f32 v[122:123], v[122:123], v[170:171]
	v_pk_add_f32 v[120:121], v[120:121], v[168:169]
	global_store_dwordx4 v[156:157], v[120:123], off offset:64
	v_pk_add_f32 v[118:119], v[118:119], v[174:175]
	v_pk_add_f32 v[116:117], v[116:117], v[172:173]
	global_store_dwordx4 v[156:157], v[116:119], off offset:512
	v_pk_add_f32 v[114:115], v[114:115], v[178:179]
	v_pk_add_f32 v[112:113], v[112:113], v[176:177]
	global_store_dwordx4 v[156:157], v[112:115], off offset:576
.LBB0_232:
	s_or_b64 exec, exec, s[20:21]
	s_nop 0
	v_add_u32_e32 v112, 16, v142
	v_cmp_gt_i32_e32 vcc, s49, v112
	s_and_saveexec_b64 s[20:21], vcc
	s_cbranch_execz .LBB0_234
	v_lshlrev_b64 v[118:119], 2, v[140:141]
	v_ashrrev_i32_e32 v113, 31, v112
	v_mov_b64_e32 v[122:123], s[10:11]
	v_lshl_add_u64 v[112:113], s[18:19], 0, v[112:113]
	v_mad_u64_u32 v[122:123], s[24:25], v112, s41, v[122:123]
	v_mov_b32_e32 v112, v123
	v_mad_u64_u32 v[112:113], s[24:25], v113, s41, v[112:113]
	v_mov_b32_e32 v123, v112
	v_lshl_add_u64 v[112:113], v[122:123], 0, v[118:119]
	v_pk_add_f32 v[110:111], v[110:111], v[166:167]
	v_pk_add_f32 v[108:109], v[108:109], v[164:165]
	global_store_dwordx4 v[112:113], v[108:111], off
	v_pk_add_f32 v[106:107], v[106:107], v[170:171]
	v_pk_add_f32 v[104:105], v[104:105], v[168:169]
	global_store_dwordx4 v[112:113], v[104:107], off offset:64
	v_pk_add_f32 v[102:103], v[102:103], v[174:175]
	v_pk_add_f32 v[100:101], v[100:101], v[172:173]
	global_store_dwordx4 v[112:113], v[100:103], off offset:512
	v_pk_add_f32 v[98:99], v[98:99], v[178:179]
	v_pk_add_f32 v[96:97], v[96:97], v[176:177]
	global_store_dwordx4 v[112:113], v[96:99], off offset:576
.LBB0_234:
	s_or_b64 exec, exec, s[20:21]
	s_nop 0
	v_add_u32_e32 v96, 32, v142
	v_cmp_gt_i32_e32 vcc, s49, v96
	s_and_saveexec_b64 s[20:21], vcc
	s_cbranch_execz .LBB0_236
	v_lshlrev_b64 v[102:103], 2, v[140:141]
	v_ashrrev_i32_e32 v97, 31, v96
	v_mov_b64_e32 v[106:107], s[10:11]
	v_lshl_add_u64 v[96:97], s[18:19], 0, v[96:97]
	v_mad_u64_u32 v[106:107], s[24:25], v96, s41, v[106:107]
	v_mov_b32_e32 v96, v107
	v_mad_u64_u32 v[96:97], s[24:25], v97, s41, v[96:97]
	v_mov_b32_e32 v107, v96
	v_lshl_add_u64 v[96:97], v[106:107], 0, v[102:103]
	v_pk_add_f32 v[94:95], v[94:95], v[166:167]
	v_pk_add_f32 v[92:93], v[92:93], v[164:165]
	global_store_dwordx4 v[96:97], v[92:95], off
	v_pk_add_f32 v[90:91], v[90:91], v[170:171]
	v_pk_add_f32 v[88:89], v[88:89], v[168:169]
	global_store_dwordx4 v[96:97], v[88:91], off offset:64
	v_pk_add_f32 v[86:87], v[86:87], v[174:175]
	v_pk_add_f32 v[84:85], v[84:85], v[172:173]
	global_store_dwordx4 v[96:97], v[84:87], off offset:512
	v_pk_add_f32 v[82:83], v[82:83], v[178:179]
	v_pk_add_f32 v[80:81], v[80:81], v[176:177]
	global_store_dwordx4 v[96:97], v[80:83], off offset:576
.LBB0_236:
	s_or_b64 exec, exec, s[20:21]
	s_nop 0
	v_add_u32_e32 v80, 48, v142
	v_cmp_gt_i32_e32 vcc, s49, v80
	s_and_saveexec_b64 s[20:21], vcc
	s_cbranch_execz .LBB0_238
	v_lshlrev_b64 v[86:87], 2, v[140:141]
	v_ashrrev_i32_e32 v81, 31, v80
	v_mov_b64_e32 v[90:91], s[10:11]
	v_lshl_add_u64 v[80:81], s[18:19], 0, v[80:81]
	v_mad_u64_u32 v[90:91], s[24:25], v80, s41, v[90:91]
	v_mov_b32_e32 v80, v91
	v_mad_u64_u32 v[80:81], s[24:25], v81, s41, v[80:81]
	v_mov_b32_e32 v91, v80
	v_lshl_add_u64 v[80:81], v[90:91], 0, v[86:87]
	v_pk_add_f32 v[78:79], v[78:79], v[166:167]
	v_pk_add_f32 v[76:77], v[76:77], v[164:165]
	global_store_dwordx4 v[80:81], v[76:79], off
	v_pk_add_f32 v[74:75], v[74:75], v[170:171]
	v_pk_add_f32 v[72:73], v[72:73], v[168:169]
	global_store_dwordx4 v[80:81], v[72:75], off offset:64
	v_pk_add_f32 v[70:71], v[70:71], v[174:175]
	v_pk_add_f32 v[68:69], v[68:69], v[172:173]
	global_store_dwordx4 v[80:81], v[68:71], off offset:512
	v_pk_add_f32 v[66:67], v[66:67], v[178:179]
	v_pk_add_f32 v[64:65], v[64:65], v[176:177]
	global_store_dwordx4 v[80:81], v[64:67], off offset:576
;     __device__ __forceinline__ void operator()(const Acc& acc, const Unit& u, int wr, int wc, int fr, int fq) const {
; #pragma unroll
;         for (int ai = 0; ai < 2; ++ai)
; #pragma unroll
;             for (int m = 0; m < 4; ++m) { const int row = ai * 128 + wr * 64 + m * 16 + fr;
;                 if (row < NMODROWS) {
; #pragma unroll
;                     for (int bj = 0; bj < 2; ++bj)
; #pragma unroll
;                         for (int n = 0; n < 2; ++n) { const int col = u.pn * 256 + bj * 128 + wc * 32 + n * 16 + fq * 4;
;                             const f32x4 b = *(const f32x4*)(bmod + (size_t)u.z * 6144 + col);
;                             *(f32x4*)(mod + ((size_t)u.z * NMODROWS + row) * 6144 + col) = acc[ai][bj][m][n] + b; } } }
;     }
.LBB0_238:
	s_or_b64 exec, exec, s[20:21]
	s_nop 0
	v_add_u32_e32 v64, 0x80, v142
	v_cmp_gt_i32_e32 vcc, s49, v64
	s_and_saveexec_b64 s[20:21], vcc
	s_cbranch_execz .LBB0_240
	v_lshlrev_b64 v[70:71], 2, v[140:141]
	v_ashrrev_i32_e32 v65, 31, v64
	v_mov_b64_e32 v[74:75], s[10:11]
	v_lshl_add_u64 v[64:65], s[18:19], 0, v[64:65]
	v_mad_u64_u32 v[74:75], s[24:25], v64, s41, v[74:75]
	v_mov_b32_e32 v64, v75
	v_mad_u64_u32 v[64:65], s[24:25], v65, s41, v[64:65]
	v_mov_b32_e32 v75, v64
	v_lshl_add_u64 v[64:65], v[74:75], 0, v[70:71]
	v_pk_add_f32 v[62:63], v[62:63], v[166:167]
	v_pk_add_f32 v[60:61], v[60:61], v[164:165]
	global_store_dwordx4 v[64:65], v[60:63], off
	v_pk_add_f32 v[58:59], v[58:59], v[170:171]
	v_pk_add_f32 v[56:57], v[56:57], v[168:169]
	global_store_dwordx4 v[64:65], v[56:59], off offset:64
	v_pk_add_f32 v[54:55], v[54:55], v[174:175]
	v_pk_add_f32 v[52:53], v[52:53], v[172:173]
	global_store_dwordx4 v[64:65], v[52:55], off offset:512
	v_pk_add_f32 v[50:51], v[50:51], v[178:179]
	v_pk_add_f32 v[48:49], v[48:49], v[176:177]
	global_store_dwordx4 v[64:65], v[48:51], off offset:576
.LBB0_240:
	s_or_b64 exec, exec, s[20:21]
	s_nop 0
	v_add_u32_e32 v48, 0x90, v142
	v_cmp_gt_i32_e32 vcc, s49, v48
	s_and_saveexec_b64 s[20:21], vcc
	s_cbranch_execz .LBB0_242
	v_lshlrev_b64 v[54:55], 2, v[140:141]
	v_ashrrev_i32_e32 v49, 31, v48
	v_mov_b64_e32 v[58:59], s[10:11]
	v_lshl_add_u64 v[48:49], s[18:19], 0, v[48:49]
	v_mad_u64_u32 v[58:59], s[24:25], v48, s41, v[58:59]
	v_mov_b32_e32 v48, v59
	v_mad_u64_u32 v[48:49], s[24:25], v49, s41, v[48:49]
	v_mov_b32_e32 v59, v48
	v_lshl_add_u64 v[48:49], v[58:59], 0, v[54:55]
	v_pk_add_f32 v[46:47], v[46:47], v[166:167]
	v_pk_add_f32 v[44:45], v[44:45], v[164:165]
	global_store_dwordx4 v[48:49], v[44:47], off
	v_pk_add_f32 v[42:43], v[42:43], v[170:171]
	v_pk_add_f32 v[40:41], v[40:41], v[168:169]
	global_store_dwordx4 v[48:49], v[40:43], off offset:64
	v_pk_add_f32 v[38:39], v[38:39], v[174:175]
	v_pk_add_f32 v[36:37], v[36:37], v[172:173]
	global_store_dwordx4 v[48:49], v[36:39], off offset:512
	v_pk_add_f32 v[34:35], v[34:35], v[178:179]
	v_pk_add_f32 v[32:33], v[32:33], v[176:177]
	global_store_dwordx4 v[48:49], v[32:35], off offset:576
.LBB0_242:
	s_or_b64 exec, exec, s[20:21]
	s_nop 0
	v_add_u32_e32 v32, 0xa0, v142
	v_cmp_gt_i32_e32 vcc, s49, v32
	s_and_saveexec_b64 s[20:21], vcc
	s_cbranch_execz .LBB0_244
	v_lshlrev_b64 v[38:39], 2, v[140:141]
	v_ashrrev_i32_e32 v33, 31, v32
	v_mov_b64_e32 v[42:43], s[10:11]
	v_lshl_add_u64 v[32:33], s[18:19], 0, v[32:33]
	v_mad_u64_u32 v[42:43], s[24:25], v32, s41, v[42:43]
	v_mov_b32_e32 v32, v43
	v_mad_u64_u32 v[32:33], s[24:25], v33, s41, v[32:33]
	v_mov_b32_e32 v43, v32
	v_lshl_add_u64 v[32:33], v[42:43], 0, v[38:39]
	v_pk_add_f32 v[30:31], v[30:31], v[166:167]
	v_pk_add_f32 v[28:29], v[28:29], v[164:165]
	global_store_dwordx4 v[32:33], v[28:31], off
	v_pk_add_f32 v[26:27], v[26:27], v[170:171]
	v_pk_add_f32 v[24:25], v[24:25], v[168:169]
	global_store_dwordx4 v[32:33], v[24:27], off offset:64
	v_pk_add_f32 v[22:23], v[22:23], v[174:175]
	v_pk_add_f32 v[20:21], v[20:21], v[172:173]
	global_store_dwordx4 v[32:33], v[20:23], off offset:512
	v_pk_add_f32 v[18:19], v[18:19], v[178:179]
	v_pk_add_f32 v[16:17], v[16:17], v[176:177]
	global_store_dwordx4 v[32:33], v[16:19], off offset:576
.LBB0_244:
	s_or_b64 exec, exec, s[20:21]
	s_nop 0
	v_add_u32_e32 v16, 0xb0, v142
	v_cmp_gt_i32_e32 vcc, s49, v16
	s_and_saveexec_b64 s[20:21], vcc
	s_cbranch_execz .LBB0_246
	v_lshlrev_b64 v[22:23], 2, v[140:141]
	v_ashrrev_i32_e32 v17, 31, v16
	v_mov_b64_e32 v[26:27], s[10:11]
	v_lshl_add_u64 v[16:17], s[18:19], 0, v[16:17]
	v_mad_u64_u32 v[26:27], s[18:19], v16, s41, v[26:27]
	v_mov_b32_e32 v16, v27
	v_mad_u64_u32 v[16:17], s[18:19], v17, s41, v[16:17]
	v_mov_b32_e32 v27, v16
	v_lshl_add_u64 v[16:17], v[26:27], 0, v[22:23]
	v_pk_add_f32 v[14:15], v[14:15], v[166:167]
	v_pk_add_f32 v[12:13], v[12:13], v[164:165]
	global_store_dwordx4 v[16:17], v[12:15], off
	v_pk_add_f32 v[10:11], v[10:11], v[170:171]
	v_pk_add_f32 v[8:9], v[8:9], v[168:169]
	global_store_dwordx4 v[16:17], v[8:11], off offset:64
	v_pk_add_f32 v[6:7], v[6:7], v[174:175]
	v_pk_add_f32 v[4:5], v[4:5], v[172:173]
	global_store_dwordx4 v[16:17], v[4:7], off offset:512
	v_pk_add_f32 v[2:3], v[2:3], v[178:179]
	v_pk_add_f32 v[0:1], v[0:1], v[176:177]
	global_store_dwordx4 v[16:17], v[0:3], off offset:576
